# GEMM K-loops (both epilogue flavours): s_nop 0 padding so that every MFMA / LDS / global instruction starts on an 8-byte boundary; attention as in the previous version
# speedup vs baseline: 1.0171x; 1.0046x over previous
; #define PG8_STAGE(bufoff, gbase, voff) do { _Pragma("unroll") for (int _i = 0; _i < 2; ++_i) \
;         __builtin_amdgcn_global_load_lds((const unsigned*)((const char*)(gbase) + (voff)[_i]), (LAS unsigned*)(lds + (bufoff) + ldsw + _i * 8192), 16, 0, 0); } while (0)
; #define PG8_LDA(dst, b, h) do { _Pragma("unroll") for (int m = 0; m < 4; ++m) _Pragma("unroll") for (int k = 0; k < 2; ++k) dst[m][k] = *(const LAS bf16x8*)(lds + PG8_SA(b, h) + aoff + m * 2048 + k * 1024); } while (0)
; #define PG8_LDB(dst, b, h) do { _Pragma("unroll") for (int n = 0; n < 2; ++n) _Pragma("unroll") for (int k = 0; k < 2; ++k) dst[n][k] = *(const LAS bf16x8*)(lds + PG8_SB(b, h) + boff + n * 2048 + k * 1024); } while (0)
; #define PG8_MMA(ai, bj, At, Bt) do { __builtin_amdgcn_s_setprio(1); _Pragma("unroll") for (int m = 0; m < 4; ++m) _Pragma("unroll") for (int n = 0; n < 2; ++n) _Pragma("unroll") for (int k = 0; k < 2; ++k) \
;         acc[ai][bj][m][n] = __builtin_amdgcn_mfma_f32_16x16x32_bf16(Bt[n][k], At[m][k], acc[ai][bj][m][n], 0, 0, 0); __builtin_amdgcn_s_setprio(0); } while (0)
; template <class Epi>
; __device__ __forceinline__ void gemm_phase(LAS unsigned char* lds, const Gemm g, const StaticOrder& S, const Epi& E, const int tid) {
;     ...
;         const bool has_next = S.next(ui + 1, nxt);
;         const char* nA = has_next ? (const char*)g.A + (size_t)nxt.pm * tstep : cA; const char* nB = has_next ? (const char*)g.Bt + (size_t)nxt.pn * tstep : cB;
;         for (int t = 0; t < nt; t += 2) {
;             const bool last = (t == nt - 2);
;             const char* a1 = cA + (size_t)(t + 1) * kstep;
;             const char* a2 = last ? nA : cA + (size_t)(t + 2) * kstep; const char* b2 = last ? nB : cB + (size_t)(t + 2) * kstep;
;             const char* a3 = a2 + kstep; const char* b3 = b2 + kstep;
;             PG8_LDB(B0, 0, 0); PG8_LDB(B1, 0, 1); PG8_SCHED; PG8_LDA(At, 0, 0); PG8_STAGE(PG8_SA(1, 1), a1 + hstep, voffA);
;             PG8_WAIT_V(8); PG8_WAIT_L(0); PG8_BAR; PG8_MMA(0, 0, At, B0); PG8_MMA(0, 1, At, B1); PG8_BAR; PG8_SCHED;
;     ...
; #pragma unroll
;         for (int a = 0; a < 2; ++a)
; #pragma unroll
;             for (int b = 0; b < 2; ++b)
; #pragma unroll
;                 for (int m = 0; m < 4; ++m)
; #pragma unroll
;                     for (int n = 0; n < 2; ++n) acc[a][b][m][n] = (f32x4){0.f, 0.f, 0.f, 0.f};
;         cur = nxt; cA = nA; cB = nB; ++ui;
.LBB0_343:
	s_add_u32 s18, s18, 0x80
	s_addc_u32 s19, s19, 0
	s_add_u32 s55, s26, 0x100
	v_mov_b32_e32 v0, 0
	s_addc_u32 s56, s27, 0
	s_mov_b32 s26, 0
	v_mov_b32_e32 v1, v0
	v_mov_b32_e32 v2, v0
	v_mov_b32_e32 v3, v0
	v_mov_b32_e32 v4, v0
	v_mov_b32_e32 v5, v0
	v_mov_b32_e32 v6, v0
	v_mov_b32_e32 v7, v0
	v_mov_b32_e32 v16, v0
	v_mov_b32_e32 v17, v0
	v_mov_b32_e32 v18, v0
	v_mov_b32_e32 v19, v0
	v_mov_b32_e32 v20, v0
	v_mov_b32_e32 v21, v0
	v_mov_b32_e32 v22, v0
	v_mov_b32_e32 v23, v0
	v_mov_b32_e32 v32, v0
	v_mov_b32_e32 v33, v0
	v_mov_b32_e32 v34, v0
	v_mov_b32_e32 v35, v0
	v_mov_b32_e32 v36, v0
	v_mov_b32_e32 v37, v0
	v_mov_b32_e32 v38, v0
	v_mov_b32_e32 v39, v0
	v_mov_b32_e32 v48, v0
	v_mov_b32_e32 v49, v0
	v_mov_b32_e32 v50, v0
	v_mov_b32_e32 v51, v0
	v_mov_b32_e32 v52, v0
	v_mov_b32_e32 v53, v0
	v_mov_b32_e32 v54, v0
	v_mov_b32_e32 v55, v0
	v_mov_b32_e32 v8, v0
	v_mov_b32_e32 v9, v0
	v_mov_b32_e32 v10, v0
	v_mov_b32_e32 v11, v0
	v_mov_b32_e32 v12, v0
	v_mov_b32_e32 v13, v0
	v_mov_b32_e32 v14, v0
	v_mov_b32_e32 v15, v0
	v_mov_b32_e32 v24, v0
	v_mov_b32_e32 v25, v0
	v_mov_b32_e32 v26, v0
	v_mov_b32_e32 v27, v0
	v_mov_b32_e32 v28, v0
	v_mov_b32_e32 v29, v0
	v_mov_b32_e32 v30, v0
	v_mov_b32_e32 v31, v0
	v_mov_b32_e32 v40, v0
	v_mov_b32_e32 v41, v0
	v_mov_b32_e32 v42, v0
	v_mov_b32_e32 v43, v0
	v_mov_b32_e32 v44, v0
	v_mov_b32_e32 v45, v0
	v_mov_b32_e32 v46, v0
	v_mov_b32_e32 v47, v0
	v_mov_b32_e32 v56, v0
	v_mov_b32_e32 v57, v0
	v_mov_b32_e32 v58, v0
	v_mov_b32_e32 v59, v0
	v_mov_b32_e32 v60, v0
	v_mov_b32_e32 v61, v0
	v_mov_b32_e32 v62, v0
	v_mov_b32_e32 v63, v0
	v_mov_b32_e32 v66, v0
	s_waitcnt vmcnt(0)
	v_mov_b32_e32 v67, v0
	v_mov_b32_e32 v68, v0
	v_mov_b32_e32 v69, v0
	v_mov_b32_e32 v70, v0
	v_mov_b32_e32 v71, v0
	v_mov_b32_e32 v72, v0
	v_mov_b32_e32 v73, v0
	v_mov_b32_e32 v82, v0
	v_mov_b32_e32 v83, v0
	v_mov_b32_e32 v84, v0
	v_mov_b32_e32 v85, v0
	v_mov_b32_e32 v86, v0
	v_mov_b32_e32 v87, v0
	v_mov_b32_e32 v88, v0
	v_mov_b32_e32 v89, v0
	v_mov_b32_e32 v98, v0
	v_mov_b32_e32 v99, v0
	v_mov_b32_e32 v100, v0
	v_mov_b32_e32 v101, v0
	v_mov_b32_e32 v102, v0
	v_mov_b32_e32 v103, v0
	v_mov_b32_e32 v104, v0
	v_mov_b32_e32 v105, v0
	v_mov_b32_e32 v114, v0
	v_mov_b32_e32 v115, v0
	v_mov_b32_e32 v116, v0
	v_mov_b32_e32 v117, v0
	v_mov_b32_e32 v118, v0
	v_mov_b32_e32 v119, v0
	v_mov_b32_e32 v120, v0
	v_mov_b32_e32 v121, v0
	v_mov_b32_e32 v74, v0
	v_mov_b32_e32 v75, v0
	v_mov_b32_e32 v76, v0
	v_mov_b32_e32 v77, v0
	v_mov_b32_e32 v78, v0
	v_mov_b32_e32 v79, v0
	v_mov_b32_e32 v80, v0
	v_mov_b32_e32 v81, v0
	v_mov_b32_e32 v90, v0
	v_mov_b32_e32 v91, v0
	v_mov_b32_e32 v92, v0
	v_mov_b32_e32 v93, v0
	v_mov_b32_e32 v94, v0
	v_mov_b32_e32 v95, v0
	v_mov_b32_e32 v96, v0
	v_mov_b32_e32 v97, v0
	v_mov_b32_e32 v106, v0
	v_mov_b32_e32 v107, v0
	v_mov_b32_e32 v108, v0
	v_mov_b32_e32 v109, v0
	v_mov_b32_e32 v110, v0
	v_mov_b32_e32 v111, v0
	v_mov_b32_e32 v112, v0
	v_mov_b32_e32 v113, v0
	v_mov_b32_e32 v122, v0
	v_mov_b32_e32 v123, v0
	v_mov_b32_e32 v124, v0
	v_mov_b32_e32 v125, v0
	v_mov_b32_e32 v126, v0
	v_mov_b32_e32 v127, v0
	v_mov_b32_e32 v128, v0
	v_mov_b32_e32 v129, v0
	v_readlane_b32 s68, v253, 13
	s_mov_b64 s[70:71], 0x80
	s_nop 0
.LBB0_344:
	s_add_i32 s57, s26, 2
	s_nop 0
	s_add_u32 s58, s18, 0x80
	s_addc_u32 s27, s19, 0
	s_cmp_eq_u32 s47, s26
	s_cselect_b32 s27, s5, s27
	s_cselect_b32 s26, s4, s58
	s_cselect_b32 s59, s17, s56
	s_cselect_b32 s58, s16, s55
	s_add_i32 s60, 0, 0x14000
	v_add_u32_e32 v154, s68, v141
	v_add_u32_e32 v170, s60, v141
	ds_read_b128 v[142:145], v154
	ds_read_b128 v[146:149], v154 offset:1024
	ds_read_b128 v[150:153], v154 offset:2048
	ds_read_b128 v[154:157], v154 offset:3072
	ds_read_b128 v[158:161], v170
	ds_read_b128 v[162:165], v170 offset:1024
	ds_read_b128 v[166:169], v170 offset:2048
	ds_read_b128 v[170:173], v170 offset:3072
	v_lshl_add_u64 v[202:203], s[18:19], 0, v[132:133]
	s_add_i32 m0, s34, 0xc000
	ds_read_b128 v[174:177], v213
	ds_read_b128 v[178:181], v213 offset:1024
	ds_read_b128 v[182:185], v213 offset:2048
	ds_read_b128 v[186:189], v213 offset:3072
	ds_read_b128 v[214:217], v213 offset:4096
	ds_read_b128 v[218:221], v213 offset:5120
	ds_read_b128 v[222:225], v213 offset:6144
	ds_read_b128 v[226:229], v213 offset:7168
	global_load_lds_dwordx4 v[202:203], off
	v_lshl_add_u64 v[202:203], s[18:19], 0, v[134:135]
	s_add_i32 m0, s34, 0xe000
	s_nop 0
	s_nop 0
	global_load_lds_dwordx4 v[202:203], off
	s_waitcnt vmcnt(8)
	s_waitcnt lgkmcnt(0)
	s_barrier
; #define PG8_STAGE(bufoff, gbase, voff) do { _Pragma("unroll") for (int _i = 0; _i < 2; ++_i) \
;         __builtin_amdgcn_global_load_lds((const unsigned*)((const char*)(gbase) + (voff)[_i]), (LAS unsigned*)(lds + (bufoff) + ldsw + _i * 8192), 16, 0, 0); } while (0)
; #define PG8_LDA(dst, b, h) do { _Pragma("unroll") for (int m = 0; m < 4; ++m) _Pragma("unroll") for (int k = 0; k < 2; ++k) dst[m][k] = *(const LAS bf16x8*)(lds + PG8_SA(b, h) + aoff + m * 2048 + k * 1024); } while (0)
; #define PG8_MMA(ai, bj, At, Bt) do { __builtin_amdgcn_s_setprio(1); _Pragma("unroll") for (int m = 0; m < 4; ++m) _Pragma("unroll") for (int n = 0; n < 2; ++n) _Pragma("unroll") for (int k = 0; k < 2; ++k) \
;         acc[ai][bj][m][n] = __builtin_amdgcn_mfma_f32_16x16x32_bf16(Bt[n][k], At[m][k], acc[ai][bj][m][n], 0, 0, 0); __builtin_amdgcn_s_setprio(0); } while (0)
; #define PG8_WAIT_V(n) asm volatile("s_waitcnt vmcnt(" #n ")" ::: "memory")
; #define PG8_WAIT_L(n) asm volatile("s_waitcnt lgkmcnt(" #n ")" ::: "memory")
; #define PG8_BAR __builtin_amdgcn_s_barrier()
; #define PG8_SCHED __builtin_amdgcn_sched_barrier(0)
; template <class Epi>
; __device__ __forceinline__ void gemm_phase(LAS unsigned char* lds, const Gemm g, const StaticOrder& S, const Epi& E, const int tid) {
;     ...
;             PG8_WAIT_V(8); PG8_WAIT_L(0); PG8_BAR; PG8_MMA(0, 0, At, B0); PG8_MMA(0, 1, At, B1); PG8_BAR; PG8_SCHED;
;             PG8_LDA(At, 0, 1); PG8_STAGE(PG8_SB(0, 0), b2, voffB); PG8_STAGE(PG8_SB(0, 1), b2 + hstep, voffB); PG8_STAGE(PG8_SA(0, 0), a2, voffA);
;             PG8_WAIT_V(8); PG8_WAIT_L(0); PG8_BAR; PG8_MMA(1, 0, At, B0); PG8_MMA(1, 1, At, B1); PG8_BAR; PG8_SCHED;
	s_setprio 1
	s_waitcnt lgkmcnt(0)
	s_nop 0
	v_mfma_f32_16x16x32_bf16 v[126:129], v[142:145], v[174:177], v[126:129]
	v_mfma_f32_16x16x32_bf16 v[122:125], v[150:153], v[174:177], v[122:125]
	v_mfma_f32_16x16x32_bf16 v[110:113], v[142:145], v[182:185], v[110:113]
	v_mfma_f32_16x16x32_bf16 v[106:109], v[150:153], v[182:185], v[106:109]
	v_mfma_f32_16x16x32_bf16 v[94:97], v[142:145], v[214:217], v[94:97]
	v_mfma_f32_16x16x32_bf16 v[90:93], v[150:153], v[214:217], v[90:93]
	v_mfma_f32_16x16x32_bf16 v[78:81], v[142:145], v[222:225], v[78:81]
	v_mfma_f32_16x16x32_bf16 v[74:77], v[150:153], v[222:225], v[74:77]
	v_mfma_f32_16x16x32_bf16 v[126:129], v[146:149], v[178:181], v[126:129]
	v_mfma_f32_16x16x32_bf16 v[122:125], v[154:157], v[178:181], v[122:125]
	v_mfma_f32_16x16x32_bf16 v[110:113], v[146:149], v[186:189], v[110:113]
	v_mfma_f32_16x16x32_bf16 v[106:109], v[154:157], v[186:189], v[106:109]
	v_mfma_f32_16x16x32_bf16 v[94:97], v[146:149], v[218:221], v[94:97]
	v_mfma_f32_16x16x32_bf16 v[90:93], v[154:157], v[218:221], v[90:93]
	v_mfma_f32_16x16x32_bf16 v[78:81], v[146:149], v[226:229], v[78:81]
	v_mfma_f32_16x16x32_bf16 v[74:77], v[154:157], v[226:229], v[74:77]
	s_setprio 0
	s_setprio 1
	v_mfma_f32_16x16x32_bf16 v[118:121], v[158:161], v[174:177], v[118:121]
	v_mfma_f32_16x16x32_bf16 v[114:117], v[166:169], v[174:177], v[114:117]
	v_mfma_f32_16x16x32_bf16 v[102:105], v[158:161], v[182:185], v[102:105]
	v_mfma_f32_16x16x32_bf16 v[98:101], v[166:169], v[182:185], v[98:101]
	v_mfma_f32_16x16x32_bf16 v[86:89], v[158:161], v[214:217], v[86:89]
	v_mfma_f32_16x16x32_bf16 v[82:85], v[166:169], v[214:217], v[82:85]
	v_mfma_f32_16x16x32_bf16 v[70:73], v[158:161], v[222:225], v[70:73]
	v_mfma_f32_16x16x32_bf16 v[66:69], v[166:169], v[222:225], v[66:69]
	v_mfma_f32_16x16x32_bf16 v[118:121], v[162:165], v[178:181], v[118:121]
	v_mfma_f32_16x16x32_bf16 v[114:117], v[170:173], v[178:181], v[114:117]
	v_mfma_f32_16x16x32_bf16 v[102:105], v[162:165], v[186:189], v[102:105]
	v_mfma_f32_16x16x32_bf16 v[98:101], v[170:173], v[186:189], v[98:101]
	v_mfma_f32_16x16x32_bf16 v[86:89], v[162:165], v[218:221], v[86:89]
	v_mfma_f32_16x16x32_bf16 v[82:85], v[170:173], v[218:221], v[82:85]
	v_mfma_f32_16x16x32_bf16 v[70:73], v[162:165], v[226:229], v[70:73]
	v_mfma_f32_16x16x32_bf16 v[66:69], v[170:173], v[226:229], v[66:69]
	s_setprio 0
	s_barrier
	s_add_i32 s61, s68, s31
	s_nop 0
	v_lshl_add_u64 v[202:203], s[58:59], 0, v[64:65]
	s_mov_b32 m0, s61
	s_nop 0
	ds_read_b128 v[174:177], v213 offset:16384
	ds_read_b128 v[178:181], v213 offset:17408
	ds_read_b128 v[182:185], v213 offset:18432
	ds_read_b128 v[186:189], v213 offset:19456
	ds_read_b128 v[214:217], v213 offset:20480
	ds_read_b128 v[218:221], v213 offset:21504
	ds_read_b128 v[222:225], v213 offset:22528
	ds_read_b128 v[226:229], v213 offset:23552
	global_load_lds_dwordx4 v[202:203], off
	s_add_i32 m0, s61, 0x2000
	v_lshl_add_u64 v[230:231], s[58:59], 0, v[130:131]
	s_add_u32 s58, s58, s10
	s_addc_u32 s59, s59, 0
	s_add_i32 s60, s60, s31
	s_nop 0
	global_load_lds_dwordx4 v[230:231], off
	v_lshl_add_u64 v[232:233], s[58:59], 0, v[64:65]
	s_mov_b32 m0, s60
	s_nop 0
	v_lshl_add_u64 v[234:235], s[58:59], 0, v[130:131]
	global_load_lds_dwordx4 v[232:233], off
	s_add_i32 m0, s60, 0x2000
	v_lshl_add_u64 v[236:237], s[26:27], 0, v[64:65]
	global_load_lds_dwordx4 v[234:235], off
	s_mov_b32 m0, s34
	s_nop 0
	v_lshl_add_u64 v[238:239], s[26:27], 0, v[130:131]
	global_load_lds_dwordx4 v[236:237], off
	s_mov_b32 m0, s35
	s_nop 0
	global_load_lds_dwordx4 v[238:239], off
	s_waitcnt vmcnt(8)
	s_waitcnt lgkmcnt(0)
	s_barrier
	s_setprio 1
	s_waitcnt lgkmcnt(0)
	s_nop 0
	v_mfma_f32_16x16x32_bf16 v[60:63], v[142:145], v[174:177], v[60:63]
	v_mfma_f32_16x16x32_bf16 v[56:59], v[150:153], v[174:177], v[56:59]
	v_mfma_f32_16x16x32_bf16 v[44:47], v[142:145], v[182:185], v[44:47]
	v_mfma_f32_16x16x32_bf16 v[40:43], v[150:153], v[182:185], v[40:43]
	v_mfma_f32_16x16x32_bf16 v[28:31], v[142:145], v[214:217], v[28:31]
	v_mfma_f32_16x16x32_bf16 v[24:27], v[150:153], v[214:217], v[24:27]
	v_mfma_f32_16x16x32_bf16 v[12:15], v[142:145], v[222:225], v[12:15]
	v_mfma_f32_16x16x32_bf16 v[8:11], v[150:153], v[222:225], v[8:11]
	v_mfma_f32_16x16x32_bf16 v[60:63], v[146:149], v[178:181], v[60:63]
	v_mfma_f32_16x16x32_bf16 v[56:59], v[154:157], v[178:181], v[56:59]
	v_mfma_f32_16x16x32_bf16 v[44:47], v[146:149], v[186:189], v[44:47]
	v_mfma_f32_16x16x32_bf16 v[40:43], v[154:157], v[186:189], v[40:43]
	v_mfma_f32_16x16x32_bf16 v[28:31], v[146:149], v[218:221], v[28:31]
	v_mfma_f32_16x16x32_bf16 v[24:27], v[154:157], v[218:221], v[24:27]
	v_mfma_f32_16x16x32_bf16 v[12:15], v[146:149], v[226:229], v[12:15]
	v_mfma_f32_16x16x32_bf16 v[8:11], v[154:157], v[226:229], v[8:11]
	s_setprio 0
	s_setprio 1
	v_mfma_f32_16x16x32_bf16 v[52:55], v[158:161], v[174:177], v[52:55]
	v_mfma_f32_16x16x32_bf16 v[48:51], v[166:169], v[174:177], v[48:51]
	v_mfma_f32_16x16x32_bf16 v[36:39], v[158:161], v[182:185], v[36:39]
	v_mfma_f32_16x16x32_bf16 v[32:35], v[166:169], v[182:185], v[32:35]
	v_mfma_f32_16x16x32_bf16 v[20:23], v[158:161], v[214:217], v[20:23]
	v_mfma_f32_16x16x32_bf16 v[16:19], v[166:169], v[214:217], v[16:19]
	v_mfma_f32_16x16x32_bf16 v[4:7], v[158:161], v[222:225], v[4:7]
	v_mfma_f32_16x16x32_bf16 v[0:3], v[166:169], v[222:225], v[0:3]
	v_mfma_f32_16x16x32_bf16 v[52:55], v[162:165], v[178:181], v[52:55]
	v_mfma_f32_16x16x32_bf16 v[48:51], v[170:173], v[178:181], v[48:51]
	v_mfma_f32_16x16x32_bf16 v[36:39], v[162:165], v[186:189], v[36:39]
	v_mfma_f32_16x16x32_bf16 v[32:35], v[170:173], v[186:189], v[32:35]
	v_mfma_f32_16x16x32_bf16 v[20:23], v[162:165], v[218:221], v[20:23]
	v_mfma_f32_16x16x32_bf16 v[16:19], v[170:173], v[218:221], v[16:19]
	v_mfma_f32_16x16x32_bf16 v[4:7], v[162:165], v[226:229], v[4:7]
	v_mfma_f32_16x16x32_bf16 v[0:3], v[170:173], v[226:229], v[0:3]
	s_setprio 0
	s_barrier
; #define PG8_STAGE(bufoff, gbase, voff) do { _Pragma("unroll") for (int _i = 0; _i < 2; ++_i) \
;         __builtin_amdgcn_global_load_lds((const unsigned*)((const char*)(gbase) + (voff)[_i]), (LAS unsigned*)(lds + (bufoff) + ldsw + _i * 8192), 16, 0, 0); } while (0)
; #define PG8_LDA(dst, b, h) do { _Pragma("unroll") for (int m = 0; m < 4; ++m) _Pragma("unroll") for (int k = 0; k < 2; ++k) dst[m][k] = *(const LAS bf16x8*)(lds + PG8_SA(b, h) + aoff + m * 2048 + k * 1024); } while (0)
; #define PG8_LDB(dst, b, h) do { _Pragma("unroll") for (int n = 0; n < 2; ++n) _Pragma("unroll") for (int k = 0; k < 2; ++k) dst[n][k] = *(const LAS bf16x8*)(lds + PG8_SB(b, h) + boff + n * 2048 + k * 1024); } while (0)
; #define PG8_MMA(ai, bj, At, Bt) do { __builtin_amdgcn_s_setprio(1); _Pragma("unroll") for (int m = 0; m < 4; ++m) _Pragma("unroll") for (int n = 0; n < 2; ++n) _Pragma("unroll") for (int k = 0; k < 2; ++k) \
;         acc[ai][bj][m][n] = __builtin_amdgcn_mfma_f32_16x16x32_bf16(Bt[n][k], At[m][k], acc[ai][bj][m][n], 0, 0, 0); __builtin_amdgcn_s_setprio(0); } while (0)
; #define PG8_WAIT_V(n) asm volatile("s_waitcnt vmcnt(" #n ")" ::: "memory")
; #define PG8_WAIT_L(n) asm volatile("s_waitcnt lgkmcnt(" #n ")" ::: "memory")
; #define PG8_BAR __builtin_amdgcn_s_barrier()
; #define PG8_SCHED __builtin_amdgcn_sched_barrier(0)
; template <class Epi>
; __device__ __forceinline__ void gemm_phase(LAS unsigned char* lds, const Gemm g, const StaticOrder& S, const Epi& E, const int tid) {
;     ...
;             PG8_LDB(B0, 1, 0); PG8_LDB(B1, 1, 1); PG8_SCHED; PG8_LDA(At, 1, 0); PG8_STAGE(PG8_SA(0, 1), a2 + hstep, voffA);
;             PG8_WAIT_V(8); PG8_WAIT_L(0); PG8_BAR; PG8_MMA(0, 0, At, B0); PG8_MMA(0, 1, At, B1); PG8_BAR; PG8_SCHED;
	s_add_i32 s58, 0, 0x18000
	s_add_i32 s59, 0, 0x1c000
	v_add_u32_e32 v154, s58, v141
	v_add_u32_e32 v170, s59, v141
	ds_read_b128 v[142:145], v154
	ds_read_b128 v[146:149], v154 offset:1024
	ds_read_b128 v[150:153], v154 offset:2048
	ds_read_b128 v[154:157], v154 offset:3072
	ds_read_b128 v[158:161], v170
	ds_read_b128 v[162:165], v170 offset:1024
	ds_read_b128 v[166:169], v170 offset:2048
	ds_read_b128 v[170:173], v170 offset:3072
	s_add_u32 s26, s26, s10
	s_addc_u32 s27, s27, 0
	s_mov_b32 m0, s36
	s_nop 0
	v_lshl_add_u64 v[240:241], s[26:27], 0, v[64:65]
	ds_read_b128 v[174:177], v213 offset:32768
	ds_read_b128 v[178:181], v213 offset:33792
	ds_read_b128 v[182:185], v213 offset:34816
	ds_read_b128 v[186:189], v213 offset:35840
	ds_read_b128 v[214:217], v213 offset:36864
	ds_read_b128 v[218:221], v213 offset:37888
	ds_read_b128 v[222:225], v213 offset:38912
	ds_read_b128 v[226:229], v213 offset:39936
	global_load_lds_dwordx4 v[240:241], off
	v_lshl_add_u64 v[240:241], s[26:27], 0, v[130:131]
	s_mov_b32 m0, s37
	s_nop 0
	global_load_lds_dwordx4 v[240:241], off
	s_waitcnt vmcnt(8)
	s_waitcnt lgkmcnt(0)
	s_barrier
	s_setprio 1
	s_waitcnt lgkmcnt(0)
	s_nop 0
	v_mfma_f32_16x16x32_bf16 v[126:129], v[142:145], v[174:177], v[126:129]
	v_mfma_f32_16x16x32_bf16 v[122:125], v[150:153], v[174:177], v[122:125]
	v_mfma_f32_16x16x32_bf16 v[110:113], v[142:145], v[182:185], v[110:113]
	v_mfma_f32_16x16x32_bf16 v[106:109], v[150:153], v[182:185], v[106:109]
	v_mfma_f32_16x16x32_bf16 v[94:97], v[142:145], v[214:217], v[94:97]
	v_mfma_f32_16x16x32_bf16 v[90:93], v[150:153], v[214:217], v[90:93]
	v_mfma_f32_16x16x32_bf16 v[78:81], v[142:145], v[222:225], v[78:81]
	v_mfma_f32_16x16x32_bf16 v[74:77], v[150:153], v[222:225], v[74:77]
	v_mfma_f32_16x16x32_bf16 v[126:129], v[146:149], v[178:181], v[126:129]
	v_mfma_f32_16x16x32_bf16 v[122:125], v[154:157], v[178:181], v[122:125]
	v_mfma_f32_16x16x32_bf16 v[110:113], v[146:149], v[186:189], v[110:113]
	v_mfma_f32_16x16x32_bf16 v[106:109], v[154:157], v[186:189], v[106:109]
	v_mfma_f32_16x16x32_bf16 v[94:97], v[146:149], v[218:221], v[94:97]
	v_mfma_f32_16x16x32_bf16 v[90:93], v[154:157], v[218:221], v[90:93]
	v_mfma_f32_16x16x32_bf16 v[78:81], v[146:149], v[226:229], v[78:81]
	v_mfma_f32_16x16x32_bf16 v[74:77], v[154:157], v[226:229], v[74:77]
	s_setprio 0
	s_setprio 1
	v_mfma_f32_16x16x32_bf16 v[118:121], v[158:161], v[174:177], v[118:121]
	v_mfma_f32_16x16x32_bf16 v[114:117], v[166:169], v[174:177], v[114:117]
	v_mfma_f32_16x16x32_bf16 v[102:105], v[158:161], v[182:185], v[102:105]
	v_mfma_f32_16x16x32_bf16 v[98:101], v[166:169], v[182:185], v[98:101]
	v_mfma_f32_16x16x32_bf16 v[86:89], v[158:161], v[214:217], v[86:89]
	v_mfma_f32_16x16x32_bf16 v[82:85], v[166:169], v[214:217], v[82:85]
	v_mfma_f32_16x16x32_bf16 v[70:73], v[158:161], v[222:225], v[70:73]
	v_mfma_f32_16x16x32_bf16 v[66:69], v[166:169], v[222:225], v[66:69]
	v_mfma_f32_16x16x32_bf16 v[118:121], v[162:165], v[178:181], v[118:121]
	v_mfma_f32_16x16x32_bf16 v[114:117], v[170:173], v[178:181], v[114:117]
	v_mfma_f32_16x16x32_bf16 v[102:105], v[162:165], v[186:189], v[102:105]
	v_mfma_f32_16x16x32_bf16 v[98:101], v[170:173], v[186:189], v[98:101]
	v_mfma_f32_16x16x32_bf16 v[86:89], v[162:165], v[218:221], v[86:89]
	v_mfma_f32_16x16x32_bf16 v[82:85], v[170:173], v[218:221], v[82:85]
	v_mfma_f32_16x16x32_bf16 v[70:73], v[162:165], v[226:229], v[70:73]
	v_mfma_f32_16x16x32_bf16 v[66:69], v[170:173], v[226:229], v[66:69]
	s_setprio 0
	s_barrier
; #define PG8_STAGE(bufoff, gbase, voff) do { _Pragma("unroll") for (int _i = 0; _i < 2; ++_i) \
;         __builtin_amdgcn_global_load_lds((const unsigned*)((const char*)(gbase) + (voff)[_i]), (LAS unsigned*)(lds + (bufoff) + ldsw + _i * 8192), 16, 0, 0); } while (0)
; #define PG8_LDA(dst, b, h) do { _Pragma("unroll") for (int m = 0; m < 4; ++m) _Pragma("unroll") for (int k = 0; k < 2; ++k) dst[m][k] = *(const LAS bf16x8*)(lds + PG8_SA(b, h) + aoff + m * 2048 + k * 1024); } while (0)
; #define PG8_MMA(ai, bj, At, Bt) do { __builtin_amdgcn_s_setprio(1); _Pragma("unroll") for (int m = 0; m < 4; ++m) _Pragma("unroll") for (int n = 0; n < 2; ++n) _Pragma("unroll") for (int k = 0; k < 2; ++k) \
;         acc[ai][bj][m][n] = __builtin_amdgcn_mfma_f32_16x16x32_bf16(Bt[n][k], At[m][k], acc[ai][bj][m][n], 0, 0, 0); __builtin_amdgcn_s_setprio(0); } while (0)
; #define PG8_WAIT_V(n) asm volatile("s_waitcnt vmcnt(" #n ")" ::: "memory")
; #define PG8_WAIT_L(n) asm volatile("s_waitcnt lgkmcnt(" #n ")" ::: "memory")
; #define PG8_BAR __builtin_amdgcn_s_barrier()
; #define PG8_SCHED __builtin_amdgcn_sched_barrier(0)
; template <class Epi>
; __device__ __forceinline__ void gemm_phase(LAS unsigned char* lds, const Gemm g, const StaticOrder& S, const Epi& E, const int tid) {
;     ...
;         for (int t = 0; t < nt; t += 2) {
;     ...
;             PG8_LDA(At, 1, 1); PG8_STAGE(PG8_SB(1, 0), b3, voffB); PG8_STAGE(PG8_SB(1, 1), b3 + hstep, voffB); PG8_STAGE(PG8_SA(1, 0), a3, voffA);
;             PG8_WAIT_V(8); PG8_WAIT_L(0); PG8_BAR; PG8_MMA(1, 0, At, B0); PG8_MMA(1, 1, At, B1); PG8_BAR; PG8_SCHED;
;         }
	s_add_i32 s26, s58, s31
	s_nop 0
	v_lshl_add_u64 v[202:203], v[202:203], 0, s[70:71]
	s_mov_b32 m0, s26
	s_nop 0
	ds_read_b128 v[174:177], v213 offset:49152
	ds_read_b128 v[178:181], v213 offset:50176
	ds_read_b128 v[182:185], v213 offset:51200
	ds_read_b128 v[186:189], v213 offset:52224
	ds_read_b128 v[214:217], v213 offset:53248
	ds_read_b128 v[218:221], v213 offset:54272
	ds_read_b128 v[222:225], v213 offset:55296
	ds_read_b128 v[226:229], v213 offset:56320
	global_load_lds_dwordx4 v[202:203], off
	v_lshl_add_u64 v[202:203], v[230:231], 0, s[70:71]
	s_add_i32 m0, s26, 0x2000
	s_add_i32 s26, s59, s31
	s_nop 0
	global_load_lds_dwordx4 v[202:203], off
	v_lshl_add_u64 v[202:203], v[232:233], 0, s[70:71]
	s_mov_b32 m0, s26
	s_nop 0
	global_load_lds_dwordx4 v[202:203], off
	v_lshl_add_u64 v[202:203], v[234:235], 0, s[70:71]
	s_add_i32 m0, s26, 0x2000
	s_nop 0
	s_nop 0
	global_load_lds_dwordx4 v[202:203], off
	v_lshl_add_u64 v[202:203], v[236:237], 0, s[70:71]
	s_mov_b32 m0, s45
	s_nop 0
	global_load_lds_dwordx4 v[202:203], off
	v_lshl_add_u64 v[202:203], v[238:239], 0, s[70:71]
	s_mov_b32 m0, s46
	s_nop 0
	global_load_lds_dwordx4 v[202:203], off
	s_waitcnt vmcnt(8)
	s_waitcnt lgkmcnt(0)
	s_barrier
	s_setprio 1
	s_waitcnt lgkmcnt(0)
	s_nop 0
	v_mfma_f32_16x16x32_bf16 v[60:63], v[142:145], v[174:177], v[60:63]
	v_mfma_f32_16x16x32_bf16 v[56:59], v[150:153], v[174:177], v[56:59]
	v_mfma_f32_16x16x32_bf16 v[44:47], v[142:145], v[182:185], v[44:47]
	v_mfma_f32_16x16x32_bf16 v[40:43], v[150:153], v[182:185], v[40:43]
	v_mfma_f32_16x16x32_bf16 v[28:31], v[142:145], v[214:217], v[28:31]
	v_mfma_f32_16x16x32_bf16 v[24:27], v[150:153], v[214:217], v[24:27]
	v_mfma_f32_16x16x32_bf16 v[12:15], v[142:145], v[222:225], v[12:15]
	v_mfma_f32_16x16x32_bf16 v[8:11], v[150:153], v[222:225], v[8:11]
	v_mfma_f32_16x16x32_bf16 v[60:63], v[146:149], v[178:181], v[60:63]
	v_mfma_f32_16x16x32_bf16 v[56:59], v[154:157], v[178:181], v[56:59]
	v_mfma_f32_16x16x32_bf16 v[44:47], v[146:149], v[186:189], v[44:47]
	v_mfma_f32_16x16x32_bf16 v[40:43], v[154:157], v[186:189], v[40:43]
	v_mfma_f32_16x16x32_bf16 v[28:31], v[146:149], v[218:221], v[28:31]
	v_mfma_f32_16x16x32_bf16 v[24:27], v[154:157], v[218:221], v[24:27]
	v_mfma_f32_16x16x32_bf16 v[12:15], v[146:149], v[226:229], v[12:15]
	v_mfma_f32_16x16x32_bf16 v[8:11], v[154:157], v[226:229], v[8:11]
	s_setprio 0
	s_setprio 1
	v_mfma_f32_16x16x32_bf16 v[52:55], v[158:161], v[174:177], v[52:55]
	v_mfma_f32_16x16x32_bf16 v[48:51], v[166:169], v[174:177], v[48:51]
	v_mfma_f32_16x16x32_bf16 v[36:39], v[158:161], v[182:185], v[36:39]
	v_mfma_f32_16x16x32_bf16 v[32:35], v[166:169], v[182:185], v[32:35]
	v_mfma_f32_16x16x32_bf16 v[20:23], v[158:161], v[214:217], v[20:23]
	v_mfma_f32_16x16x32_bf16 v[16:19], v[166:169], v[214:217], v[16:19]
	v_mfma_f32_16x16x32_bf16 v[4:7], v[158:161], v[222:225], v[4:7]
	v_mfma_f32_16x16x32_bf16 v[0:3], v[166:169], v[222:225], v[0:3]
	v_mfma_f32_16x16x32_bf16 v[52:55], v[162:165], v[178:181], v[52:55]
	v_mfma_f32_16x16x32_bf16 v[48:51], v[170:173], v[178:181], v[48:51]
	v_mfma_f32_16x16x32_bf16 v[36:39], v[162:165], v[186:189], v[36:39]
	v_mfma_f32_16x16x32_bf16 v[32:35], v[170:173], v[186:189], v[32:35]
	v_mfma_f32_16x16x32_bf16 v[20:23], v[162:165], v[218:221], v[20:23]
	v_mfma_f32_16x16x32_bf16 v[16:19], v[170:173], v[218:221], v[16:19]
	v_mfma_f32_16x16x32_bf16 v[4:7], v[162:165], v[226:229], v[4:7]
	v_mfma_f32_16x16x32_bf16 v[0:3], v[170:173], v[226:229], v[0:3]
	s_setprio 0
	s_barrier
	s_add_u32 s18, s18, 0x100
	s_addc_u32 s19, s19, 0
	s_nop 0
	s_add_u32 s55, s55, 0x100
	s_addc_u32 s56, s56, 0
	s_cmp_ge_u32 s57, s39
	s_mov_b32 s26, s57
	s_cbranch_scc0 .LBB0_344
	s_and_b64 vcc, exec, s[14:15]
	s_cbranch_vccz .LBB0_347
	s_barrier

; #define PG8_STAGE(bufoff, gbase, voff) do { _Pragma("unroll") for (int _i = 0; _i < 2; ++_i) \
;         __builtin_amdgcn_global_load_lds((const unsigned*)((const char*)(gbase) + (voff)[_i]), (LAS unsigned*)(lds + (bufoff) + ldsw + _i * 8192), 16, 0, 0); } while (0)
; #define PG8_LDA(dst, b, h) do { _Pragma("unroll") for (int m = 0; m < 4; ++m) _Pragma("unroll") for (int k = 0; k < 2; ++k) dst[m][k] = *(const LAS bf16x8*)(lds + PG8_SA(b, h) + aoff + m * 2048 + k * 1024); } while (0)
; #define PG8_LDB(dst, b, h) do { _Pragma("unroll") for (int n = 0; n < 2; ++n) _Pragma("unroll") for (int k = 0; k < 2; ++k) dst[n][k] = *(const LAS bf16x8*)(lds + PG8_SB(b, h) + boff + n * 2048 + k * 1024); } while (0)
; #define PG8_SCHED __builtin_amdgcn_sched_barrier(0)
; template <class Epi>
; __device__ __forceinline__ void gemm_phase(LAS unsigned char* lds, const Gemm g, const StaticOrder& S, const Epi& E, const int tid) {
;     ...
;             const bool last = (t == nt - 2);
;             const char* a1 = cA + (size_t)(t + 1) * kstep;
;             const char* a2 = last ? nA : cA + (size_t)(t + 2) * kstep; const char* b2 = last ? nB : cB + (size_t)(t + 2) * kstep;
;             const char* a3 = a2 + kstep; const char* b3 = b2 + kstep;
;             PG8_LDB(B0, 0, 0); PG8_LDB(B1, 0, 1); PG8_SCHED; PG8_LDA(At, 0, 0); PG8_STAGE(PG8_SA(1, 1), a1 + hstep, voffA);
;     ...
;         for (int a = 0; a < 2; ++a)
; #pragma unroll
;             for (int b = 0; b < 2; ++b)
; #pragma unroll
;                 for (int m = 0; m < 4; ++m)
; #pragma unroll
;                     for (int n = 0; n < 2; ++n) acc[a][b][m][n] = (f32x4){0.f, 0.f, 0.f, 0.f};
;         cur = nxt; cA = nA; cB = nB; ++ui;
.LBB0_434:
	s_add_u32 s0, s36, 0x80
	s_addc_u32 s1, s37, 0
	s_add_u32 s8, s2, 0x100
	v_mov_b32_e32 v0, 0
	s_addc_u32 s9, s3, 0
	s_mov_b32 s2, 0
	v_mov_b32_e32 v1, v0
	v_mov_b32_e32 v2, v0
	v_mov_b32_e32 v3, v0
	v_mov_b32_e32 v4, v0
	v_mov_b32_e32 v5, v0
	v_mov_b32_e32 v6, v0
	v_mov_b32_e32 v7, v0
	v_mov_b32_e32 v16, v0
	v_mov_b32_e32 v17, v0
	v_mov_b32_e32 v18, v0
	v_mov_b32_e32 v19, v0
	s_waitcnt lgkmcnt(0)
	v_mov_b32_e32 v20, v0
	v_mov_b32_e32 v21, v0
	v_mov_b32_e32 v22, v0
	v_mov_b32_e32 v23, v0
	v_mov_b32_e32 v32, v0
	v_mov_b32_e32 v33, v0
	v_mov_b32_e32 v34, v0
	v_mov_b32_e32 v35, v0
	v_mov_b32_e32 v36, v0
	v_mov_b32_e32 v37, v0
	v_mov_b32_e32 v38, v0
	v_mov_b32_e32 v39, v0
	v_mov_b32_e32 v48, v0
	v_mov_b32_e32 v49, v0
	v_mov_b32_e32 v50, v0
	v_mov_b32_e32 v51, v0
	v_mov_b32_e32 v52, v0
	v_mov_b32_e32 v53, v0
	v_mov_b32_e32 v54, v0
	v_mov_b32_e32 v55, v0
	v_mov_b32_e32 v8, v0
	v_mov_b32_e32 v9, v0
	v_mov_b32_e32 v10, v0
	v_mov_b32_e32 v11, v0
	v_mov_b32_e32 v12, v0
	v_mov_b32_e32 v13, v0
	v_mov_b32_e32 v14, v0
	v_mov_b32_e32 v15, v0
	v_mov_b32_e32 v24, v0
	v_mov_b32_e32 v25, v0
	v_mov_b32_e32 v26, v0
	v_mov_b32_e32 v27, v0
	v_mov_b32_e32 v28, v0
	v_mov_b32_e32 v29, v0
	v_mov_b32_e32 v30, v0
	v_mov_b32_e32 v31, v0
	v_mov_b32_e32 v40, v0
	v_mov_b32_e32 v41, v0
	v_mov_b32_e32 v42, v0
	v_mov_b32_e32 v43, v0
	v_mov_b32_e32 v44, v0
	v_mov_b32_e32 v45, v0
	v_mov_b32_e32 v46, v0
	v_mov_b32_e32 v47, v0
	v_mov_b32_e32 v56, v0
	v_mov_b32_e32 v57, v0
	v_mov_b32_e32 v58, v0
	v_mov_b32_e32 v59, v0
	v_mov_b32_e32 v60, v0
	v_mov_b32_e32 v61, v0
	v_mov_b32_e32 v62, v0
	v_mov_b32_e32 v63, v0
	v_mov_b32_e32 v66, v0
	s_waitcnt vmcnt(0)
	v_mov_b32_e32 v67, v0
	v_mov_b32_e32 v68, v0
	v_mov_b32_e32 v69, v0
	v_mov_b32_e32 v70, v0
	v_mov_b32_e32 v71, v0
	v_mov_b32_e32 v72, v0
	v_mov_b32_e32 v73, v0
	v_mov_b32_e32 v82, v0
	v_mov_b32_e32 v83, v0
	v_mov_b32_e32 v84, v0
	v_mov_b32_e32 v85, v0
	v_mov_b32_e32 v86, v0
	v_mov_b32_e32 v87, v0
	v_mov_b32_e32 v88, v0
	v_mov_b32_e32 v89, v0
	v_mov_b32_e32 v98, v0
	v_mov_b32_e32 v99, v0
	v_mov_b32_e32 v100, v0
	v_mov_b32_e32 v101, v0
	v_mov_b32_e32 v102, v0
	v_mov_b32_e32 v103, v0
	v_mov_b32_e32 v104, v0
	v_mov_b32_e32 v105, v0
	v_mov_b32_e32 v114, v0
	v_mov_b32_e32 v115, v0
	v_mov_b32_e32 v116, v0
	v_mov_b32_e32 v117, v0
	v_mov_b32_e32 v118, v0
	v_mov_b32_e32 v119, v0
	v_mov_b32_e32 v120, v0
	v_mov_b32_e32 v121, v0
	v_mov_b32_e32 v74, v0
	v_mov_b32_e32 v75, v0
	v_mov_b32_e32 v76, v0
	v_mov_b32_e32 v77, v0
	v_mov_b32_e32 v78, v0
	v_mov_b32_e32 v79, v0
	v_mov_b32_e32 v80, v0
	v_mov_b32_e32 v81, v0
	v_mov_b32_e32 v90, v0
	v_mov_b32_e32 v91, v0
	v_mov_b32_e32 v92, v0
	v_mov_b32_e32 v93, v0
	v_mov_b32_e32 v94, v0
	v_mov_b32_e32 v95, v0
	v_mov_b32_e32 v96, v0
	v_mov_b32_e32 v97, v0
	v_mov_b32_e32 v106, v0
	v_mov_b32_e32 v107, v0
	v_mov_b32_e32 v108, v0
	v_mov_b32_e32 v109, v0
	v_mov_b32_e32 v110, v0
	v_mov_b32_e32 v111, v0
	v_mov_b32_e32 v112, v0
	v_mov_b32_e32 v113, v0
	v_mov_b32_e32 v122, v0
	v_mov_b32_e32 v123, v0
	v_mov_b32_e32 v124, v0
	v_mov_b32_e32 v125, v0
	v_mov_b32_e32 v126, v0
	v_mov_b32_e32 v127, v0
	v_mov_b32_e32 v128, v0
	v_mov_b32_e32 v129, v0
	v_readlane_b32 s83, v253, 13
	s_mov_b64 s[86:87], 0x80
	s_nop 0
.LBB0_435:
	s_add_i32 s36, s2, 2
	s_nop 0
	s_add_u32 s37, s0, 0x80
	s_addc_u32 s3, s1, 0
	s_cmp_eq_u32 s68, s2
	s_cselect_b32 s3, s31, s3
	s_cselect_b32 s2, s30, s37
	s_cselect_b32 s79, s35, s9
	s_cselect_b32 s78, s34, s8
	s_add_i32 s37, 0, 0x14000
	v_add_u32_e32 v162, s83, v141
	v_add_u32_e32 v177, s37, v141
	ds_read_b128 v[150:153], v162
	ds_read_b128 v[154:157], v162 offset:1024
	ds_read_b128 v[158:161], v162 offset:2048
	ds_read_b128 v[162:165], v162 offset:3072
	ds_read_b128 v[166:169], v177
	ds_read_b128 v[170:173], v177 offset:1024
	ds_read_b128 v[178:181], v177 offset:2048
	ds_read_b128 v[182:185], v177 offset:3072
	v_lshl_add_u64 v[240:241], s[0:1], 0, v[146:147]
	s_add_i32 m0, s61, 0xc000
	ds_read_b128 v[186:189], v176
	ds_read_b128 v[212:215], v176 offset:1024
	ds_read_b128 v[216:219], v176 offset:2048
	ds_read_b128 v[220:223], v176 offset:3072
	ds_read_b128 v[224:227], v176 offset:4096
	ds_read_b128 v[228:231], v176 offset:5120
	ds_read_b128 v[232:235], v176 offset:6144
	ds_read_b128 v[236:239], v176 offset:7168
	global_load_lds_dwordx4 v[240:241], off
	v_lshl_add_u64 v[240:241], s[0:1], 0, v[148:149]
	s_add_i32 m0, s61, 0xe000
	s_nop 0
	s_nop 0
	global_load_lds_dwordx4 v[240:241], off
	s_waitcnt vmcnt(8)
	s_waitcnt lgkmcnt(0)
	s_barrier
; #define PG8_STAGE(bufoff, gbase, voff) do { _Pragma("unroll") for (int _i = 0; _i < 2; ++_i) \
;         __builtin_amdgcn_global_load_lds((const unsigned*)((const char*)(gbase) + (voff)[_i]), (LAS unsigned*)(lds + (bufoff) + ldsw + _i * 8192), 16, 0, 0); } while (0)
; #define PG8_LDA(dst, b, h) do { _Pragma("unroll") for (int m = 0; m < 4; ++m) _Pragma("unroll") for (int k = 0; k < 2; ++k) dst[m][k] = *(const LAS bf16x8*)(lds + PG8_SA(b, h) + aoff + m * 2048 + k * 1024); } while (0)
; #define PG8_MMA(ai, bj, At, Bt) do { __builtin_amdgcn_s_setprio(1); _Pragma("unroll") for (int m = 0; m < 4; ++m) _Pragma("unroll") for (int n = 0; n < 2; ++n) _Pragma("unroll") for (int k = 0; k < 2; ++k) \
;         acc[ai][bj][m][n] = __builtin_amdgcn_mfma_f32_16x16x32_bf16(Bt[n][k], At[m][k], acc[ai][bj][m][n], 0, 0, 0); __builtin_amdgcn_s_setprio(0); } while (0)
; #define PG8_WAIT_V(n) asm volatile("s_waitcnt vmcnt(" #n ")" ::: "memory")
; #define PG8_WAIT_L(n) asm volatile("s_waitcnt lgkmcnt(" #n ")" ::: "memory")
; #define PG8_BAR __builtin_amdgcn_s_barrier()
; #define PG8_SCHED __builtin_amdgcn_sched_barrier(0)
; template <class Epi>
; __device__ __forceinline__ void gemm_phase(LAS unsigned char* lds, const Gemm g, const StaticOrder& S, const Epi& E, const int tid) {
;     ...
;             PG8_WAIT_V(8); PG8_WAIT_L(0); PG8_BAR; PG8_MMA(0, 0, At, B0); PG8_MMA(0, 1, At, B1); PG8_BAR; PG8_SCHED;
;             PG8_LDA(At, 0, 1); PG8_STAGE(PG8_SB(0, 0), b2, voffB); PG8_STAGE(PG8_SB(0, 1), b2 + hstep, voffB); PG8_STAGE(PG8_SA(0, 0), a2, voffA);
;             PG8_WAIT_V(8); PG8_WAIT_L(0); PG8_BAR; PG8_MMA(1, 0, At, B0); PG8_MMA(1, 1, At, B1); PG8_BAR; PG8_SCHED;
	s_setprio 1
	s_waitcnt lgkmcnt(0)
	s_nop 0
	v_mfma_f32_16x16x32_bf16 v[126:129], v[150:153], v[186:189], v[126:129]
	v_mfma_f32_16x16x32_bf16 v[122:125], v[158:161], v[186:189], v[122:125]
	v_mfma_f32_16x16x32_bf16 v[110:113], v[150:153], v[216:219], v[110:113]
	v_mfma_f32_16x16x32_bf16 v[106:109], v[158:161], v[216:219], v[106:109]
	v_mfma_f32_16x16x32_bf16 v[94:97], v[150:153], v[224:227], v[94:97]
	v_mfma_f32_16x16x32_bf16 v[90:93], v[158:161], v[224:227], v[90:93]
	v_mfma_f32_16x16x32_bf16 v[78:81], v[150:153], v[232:235], v[78:81]
	v_mfma_f32_16x16x32_bf16 v[74:77], v[158:161], v[232:235], v[74:77]
	v_mfma_f32_16x16x32_bf16 v[126:129], v[154:157], v[212:215], v[126:129]
	v_mfma_f32_16x16x32_bf16 v[122:125], v[162:165], v[212:215], v[122:125]
	v_mfma_f32_16x16x32_bf16 v[110:113], v[154:157], v[220:223], v[110:113]
	v_mfma_f32_16x16x32_bf16 v[106:109], v[162:165], v[220:223], v[106:109]
	v_mfma_f32_16x16x32_bf16 v[94:97], v[154:157], v[228:231], v[94:97]
	v_mfma_f32_16x16x32_bf16 v[90:93], v[162:165], v[228:231], v[90:93]
	v_mfma_f32_16x16x32_bf16 v[78:81], v[154:157], v[236:239], v[78:81]
	v_mfma_f32_16x16x32_bf16 v[74:77], v[162:165], v[236:239], v[74:77]
	s_setprio 0
	s_setprio 1
	v_mfma_f32_16x16x32_bf16 v[118:121], v[166:169], v[186:189], v[118:121]
	v_mfma_f32_16x16x32_bf16 v[114:117], v[178:181], v[186:189], v[114:117]
	v_mfma_f32_16x16x32_bf16 v[102:105], v[166:169], v[216:219], v[102:105]
	v_mfma_f32_16x16x32_bf16 v[98:101], v[178:181], v[216:219], v[98:101]
	v_mfma_f32_16x16x32_bf16 v[86:89], v[166:169], v[224:227], v[86:89]
	v_mfma_f32_16x16x32_bf16 v[82:85], v[178:181], v[224:227], v[82:85]
	v_mfma_f32_16x16x32_bf16 v[70:73], v[166:169], v[232:235], v[70:73]
	v_mfma_f32_16x16x32_bf16 v[66:69], v[178:181], v[232:235], v[66:69]
	v_mfma_f32_16x16x32_bf16 v[118:121], v[170:173], v[212:215], v[118:121]
	v_mfma_f32_16x16x32_bf16 v[114:117], v[182:185], v[212:215], v[114:117]
	v_mfma_f32_16x16x32_bf16 v[102:105], v[170:173], v[220:223], v[102:105]
	v_mfma_f32_16x16x32_bf16 v[98:101], v[182:185], v[220:223], v[98:101]
	v_mfma_f32_16x16x32_bf16 v[86:89], v[170:173], v[228:231], v[86:89]
	v_mfma_f32_16x16x32_bf16 v[82:85], v[182:185], v[228:231], v[82:85]
	v_mfma_f32_16x16x32_bf16 v[70:73], v[170:173], v[236:239], v[70:73]
	v_mfma_f32_16x16x32_bf16 v[66:69], v[182:185], v[236:239], v[66:69]
	s_setprio 0
	s_barrier
	s_add_i32 s38, s83, s60
	s_nop 0
	v_lshl_add_u64 v[240:241], s[78:79], 0, v[64:65]
	s_mov_b32 m0, s38
	s_nop 0
	ds_read_b128 v[186:189], v176 offset:16384
	ds_read_b128 v[212:215], v176 offset:17408
	ds_read_b128 v[216:219], v176 offset:18432
	ds_read_b128 v[220:223], v176 offset:19456
	ds_read_b128 v[224:227], v176 offset:20480
	ds_read_b128 v[228:231], v176 offset:21504
	ds_read_b128 v[232:235], v176 offset:22528
	ds_read_b128 v[236:239], v176 offset:23552
	global_load_lds_dwordx4 v[240:241], off
	s_add_i32 m0, s38, 0x2000
	v_lshl_add_u64 v[242:243], s[78:79], 0, v[134:135]
	s_add_u32 s78, s78, s80
	s_addc_u32 s79, s79, 0
	s_add_i32 s37, s37, s60
	s_nop 0
	global_load_lds_dwordx4 v[242:243], off
	v_lshl_add_u64 v[244:245], s[78:79], 0, v[64:65]
	s_mov_b32 m0, s37
	s_nop 0
	v_lshl_add_u64 v[246:247], s[78:79], 0, v[134:135]
	global_load_lds_dwordx4 v[244:245], off
	s_add_i32 m0, s37, 0x2000
	v_lshl_add_u64 v[248:249], s[2:3], 0, v[130:131]
	global_load_lds_dwordx4 v[246:247], off
	s_mov_b32 m0, s61
	s_nop 0
	v_lshl_add_u64 v[250:251], s[2:3], 0, v[132:133]
	global_load_lds_dwordx4 v[248:249], off
	s_mov_b32 m0, s62
	s_nop 0
	global_load_lds_dwordx4 v[250:251], off
	s_waitcnt vmcnt(8)
	s_waitcnt lgkmcnt(0)
	s_barrier
	s_setprio 1
	s_waitcnt lgkmcnt(0)
	s_nop 0
	v_mfma_f32_16x16x32_bf16 v[60:63], v[150:153], v[186:189], v[60:63]
	v_mfma_f32_16x16x32_bf16 v[56:59], v[158:161], v[186:189], v[56:59]
	v_mfma_f32_16x16x32_bf16 v[44:47], v[150:153], v[216:219], v[44:47]
	v_mfma_f32_16x16x32_bf16 v[40:43], v[158:161], v[216:219], v[40:43]
	v_mfma_f32_16x16x32_bf16 v[28:31], v[150:153], v[224:227], v[28:31]
	v_mfma_f32_16x16x32_bf16 v[24:27], v[158:161], v[224:227], v[24:27]
	v_mfma_f32_16x16x32_bf16 v[12:15], v[150:153], v[232:235], v[12:15]
	v_mfma_f32_16x16x32_bf16 v[8:11], v[158:161], v[232:235], v[8:11]
	v_mfma_f32_16x16x32_bf16 v[60:63], v[154:157], v[212:215], v[60:63]
	v_mfma_f32_16x16x32_bf16 v[56:59], v[162:165], v[212:215], v[56:59]
	v_mfma_f32_16x16x32_bf16 v[44:47], v[154:157], v[220:223], v[44:47]
	v_mfma_f32_16x16x32_bf16 v[40:43], v[162:165], v[220:223], v[40:43]
	v_mfma_f32_16x16x32_bf16 v[28:31], v[154:157], v[228:231], v[28:31]
	v_mfma_f32_16x16x32_bf16 v[24:27], v[162:165], v[228:231], v[24:27]
	v_mfma_f32_16x16x32_bf16 v[12:15], v[154:157], v[236:239], v[12:15]
	v_mfma_f32_16x16x32_bf16 v[8:11], v[162:165], v[236:239], v[8:11]
	s_setprio 0
	s_setprio 1
	v_mfma_f32_16x16x32_bf16 v[52:55], v[166:169], v[186:189], v[52:55]
	v_mfma_f32_16x16x32_bf16 v[48:51], v[178:181], v[186:189], v[48:51]
	v_mfma_f32_16x16x32_bf16 v[36:39], v[166:169], v[216:219], v[36:39]
	v_mfma_f32_16x16x32_bf16 v[32:35], v[178:181], v[216:219], v[32:35]
	v_mfma_f32_16x16x32_bf16 v[20:23], v[166:169], v[224:227], v[20:23]
	v_mfma_f32_16x16x32_bf16 v[16:19], v[178:181], v[224:227], v[16:19]
	v_mfma_f32_16x16x32_bf16 v[4:7], v[166:169], v[232:235], v[4:7]
	v_mfma_f32_16x16x32_bf16 v[0:3], v[178:181], v[232:235], v[0:3]
	v_mfma_f32_16x16x32_bf16 v[52:55], v[170:173], v[212:215], v[52:55]
	v_mfma_f32_16x16x32_bf16 v[48:51], v[182:185], v[212:215], v[48:51]
	v_mfma_f32_16x16x32_bf16 v[36:39], v[170:173], v[220:223], v[36:39]
	v_mfma_f32_16x16x32_bf16 v[32:35], v[182:185], v[220:223], v[32:35]
	v_mfma_f32_16x16x32_bf16 v[20:23], v[170:173], v[228:231], v[20:23]
	v_mfma_f32_16x16x32_bf16 v[16:19], v[182:185], v[228:231], v[16:19]
	v_mfma_f32_16x16x32_bf16 v[4:7], v[170:173], v[236:239], v[4:7]
	v_mfma_f32_16x16x32_bf16 v[0:3], v[182:185], v[236:239], v[0:3]
	s_setprio 0
	s_barrier
; #define PG8_STAGE(bufoff, gbase, voff) do { _Pragma("unroll") for (int _i = 0; _i < 2; ++_i) \
;         __builtin_amdgcn_global_load_lds((const unsigned*)((const char*)(gbase) + (voff)[_i]), (LAS unsigned*)(lds + (bufoff) + ldsw + _i * 8192), 16, 0, 0); } while (0)
; #define PG8_LDA(dst, b, h) do { _Pragma("unroll") for (int m = 0; m < 4; ++m) _Pragma("unroll") for (int k = 0; k < 2; ++k) dst[m][k] = *(const LAS bf16x8*)(lds + PG8_SA(b, h) + aoff + m * 2048 + k * 1024); } while (0)
; #define PG8_LDB(dst, b, h) do { _Pragma("unroll") for (int n = 0; n < 2; ++n) _Pragma("unroll") for (int k = 0; k < 2; ++k) dst[n][k] = *(const LAS bf16x8*)(lds + PG8_SB(b, h) + boff + n * 2048 + k * 1024); } while (0)
; #define PG8_MMA(ai, bj, At, Bt) do { __builtin_amdgcn_s_setprio(1); _Pragma("unroll") for (int m = 0; m < 4; ++m) _Pragma("unroll") for (int n = 0; n < 2; ++n) _Pragma("unroll") for (int k = 0; k < 2; ++k) \
;         acc[ai][bj][m][n] = __builtin_amdgcn_mfma_f32_16x16x32_bf16(Bt[n][k], At[m][k], acc[ai][bj][m][n], 0, 0, 0); __builtin_amdgcn_s_setprio(0); } while (0)
; #define PG8_WAIT_V(n) asm volatile("s_waitcnt vmcnt(" #n ")" ::: "memory")
; #define PG8_WAIT_L(n) asm volatile("s_waitcnt lgkmcnt(" #n ")" ::: "memory")
; #define PG8_BAR __builtin_amdgcn_s_barrier()
; #define PG8_SCHED __builtin_amdgcn_sched_barrier(0)
; template <class Epi>
; __device__ __forceinline__ void gemm_phase(LAS unsigned char* lds, const Gemm g, const StaticOrder& S, const Epi& E, const int tid) {
;     ...
;             PG8_LDB(B0, 1, 0); PG8_LDB(B1, 1, 1); PG8_SCHED; PG8_LDA(At, 1, 0); PG8_STAGE(PG8_SA(0, 1), a2 + hstep, voffA);
;             PG8_WAIT_V(8); PG8_WAIT_L(0); PG8_BAR; PG8_MMA(0, 0, At, B0); PG8_MMA(0, 1, At, B1); PG8_BAR; PG8_SCHED;
	s_add_i32 s37, 0, 0x18000
	s_add_i32 s38, 0, 0x1c000
	v_add_u32_e32 v162, s37, v141
	v_add_u32_e32 v177, s38, v141
	ds_read_b128 v[150:153], v162
	ds_read_b128 v[154:157], v162 offset:1024
	ds_read_b128 v[158:161], v162 offset:2048
	ds_read_b128 v[162:165], v162 offset:3072
	ds_read_b128 v[166:169], v177
	ds_read_b128 v[170:173], v177 offset:1024
	ds_read_b128 v[178:181], v177 offset:2048
	ds_read_b128 v[182:185], v177 offset:3072
	s_add_u32 s2, s2, s80
	s_addc_u32 s3, s3, 0
	s_mov_b32 m0, s63
	s_nop 0
	v_lshl_add_u64 v[202:203], s[2:3], 0, v[130:131]
	ds_read_b128 v[186:189], v176 offset:32768
	ds_read_b128 v[212:215], v176 offset:33792
	ds_read_b128 v[216:219], v176 offset:34816
	ds_read_b128 v[220:223], v176 offset:35840
	ds_read_b128 v[224:227], v176 offset:36864
	ds_read_b128 v[228:231], v176 offset:37888
	ds_read_b128 v[232:235], v176 offset:38912
	ds_read_b128 v[236:239], v176 offset:39936
	global_load_lds_dwordx4 v[202:203], off
	v_lshl_add_u64 v[202:203], s[2:3], 0, v[132:133]
	s_mov_b32 m0, s64
	s_nop 0
	global_load_lds_dwordx4 v[202:203], off
	s_waitcnt vmcnt(8)
	s_waitcnt lgkmcnt(0)
	s_barrier
	s_setprio 1
	s_waitcnt lgkmcnt(0)
	s_nop 0
	v_mfma_f32_16x16x32_bf16 v[126:129], v[150:153], v[186:189], v[126:129]
	v_mfma_f32_16x16x32_bf16 v[122:125], v[158:161], v[186:189], v[122:125]
	v_mfma_f32_16x16x32_bf16 v[110:113], v[150:153], v[216:219], v[110:113]
	v_mfma_f32_16x16x32_bf16 v[106:109], v[158:161], v[216:219], v[106:109]
	v_mfma_f32_16x16x32_bf16 v[94:97], v[150:153], v[224:227], v[94:97]
	v_mfma_f32_16x16x32_bf16 v[90:93], v[158:161], v[224:227], v[90:93]
	v_mfma_f32_16x16x32_bf16 v[78:81], v[150:153], v[232:235], v[78:81]
	v_mfma_f32_16x16x32_bf16 v[74:77], v[158:161], v[232:235], v[74:77]
	v_mfma_f32_16x16x32_bf16 v[126:129], v[154:157], v[212:215], v[126:129]
	v_mfma_f32_16x16x32_bf16 v[122:125], v[162:165], v[212:215], v[122:125]
	v_mfma_f32_16x16x32_bf16 v[110:113], v[154:157], v[220:223], v[110:113]
	v_mfma_f32_16x16x32_bf16 v[106:109], v[162:165], v[220:223], v[106:109]
	v_mfma_f32_16x16x32_bf16 v[94:97], v[154:157], v[228:231], v[94:97]
	v_mfma_f32_16x16x32_bf16 v[90:93], v[162:165], v[228:231], v[90:93]
	v_mfma_f32_16x16x32_bf16 v[78:81], v[154:157], v[236:239], v[78:81]
	v_mfma_f32_16x16x32_bf16 v[74:77], v[162:165], v[236:239], v[74:77]
	s_setprio 0
	s_setprio 1
	v_mfma_f32_16x16x32_bf16 v[118:121], v[166:169], v[186:189], v[118:121]
	v_mfma_f32_16x16x32_bf16 v[114:117], v[178:181], v[186:189], v[114:117]
	v_mfma_f32_16x16x32_bf16 v[102:105], v[166:169], v[216:219], v[102:105]
	v_mfma_f32_16x16x32_bf16 v[98:101], v[178:181], v[216:219], v[98:101]
	v_mfma_f32_16x16x32_bf16 v[86:89], v[166:169], v[224:227], v[86:89]
	v_mfma_f32_16x16x32_bf16 v[82:85], v[178:181], v[224:227], v[82:85]
	v_mfma_f32_16x16x32_bf16 v[70:73], v[166:169], v[232:235], v[70:73]
	v_mfma_f32_16x16x32_bf16 v[66:69], v[178:181], v[232:235], v[66:69]
	v_mfma_f32_16x16x32_bf16 v[118:121], v[170:173], v[212:215], v[118:121]
	v_mfma_f32_16x16x32_bf16 v[114:117], v[182:185], v[212:215], v[114:117]
	v_mfma_f32_16x16x32_bf16 v[102:105], v[170:173], v[220:223], v[102:105]
	v_mfma_f32_16x16x32_bf16 v[98:101], v[182:185], v[220:223], v[98:101]
	v_mfma_f32_16x16x32_bf16 v[86:89], v[170:173], v[228:231], v[86:89]
	v_mfma_f32_16x16x32_bf16 v[82:85], v[182:185], v[228:231], v[82:85]
	v_mfma_f32_16x16x32_bf16 v[70:73], v[170:173], v[236:239], v[70:73]
	v_mfma_f32_16x16x32_bf16 v[66:69], v[182:185], v[236:239], v[66:69]
	s_setprio 0
	s_barrier
; #define PG8_STAGE(bufoff, gbase, voff) do { _Pragma("unroll") for (int _i = 0; _i < 2; ++_i) \
;         __builtin_amdgcn_global_load_lds((const unsigned*)((const char*)(gbase) + (voff)[_i]), (LAS unsigned*)(lds + (bufoff) + ldsw + _i * 8192), 16, 0, 0); } while (0)
; #define PG8_LDA(dst, b, h) do { _Pragma("unroll") for (int m = 0; m < 4; ++m) _Pragma("unroll") for (int k = 0; k < 2; ++k) dst[m][k] = *(const LAS bf16x8*)(lds + PG8_SA(b, h) + aoff + m * 2048 + k * 1024); } while (0)
; #define PG8_MMA(ai, bj, At, Bt) do { __builtin_amdgcn_s_setprio(1); _Pragma("unroll") for (int m = 0; m < 4; ++m) _Pragma("unroll") for (int n = 0; n < 2; ++n) _Pragma("unroll") for (int k = 0; k < 2; ++k) \
;         acc[ai][bj][m][n] = __builtin_amdgcn_mfma_f32_16x16x32_bf16(Bt[n][k], At[m][k], acc[ai][bj][m][n], 0, 0, 0); __builtin_amdgcn_s_setprio(0); } while (0)
; #define PG8_WAIT_V(n) asm volatile("s_waitcnt vmcnt(" #n ")" ::: "memory")
; #define PG8_WAIT_L(n) asm volatile("s_waitcnt lgkmcnt(" #n ")" ::: "memory")
; #define PG8_BAR __builtin_amdgcn_s_barrier()
; #define PG8_SCHED __builtin_amdgcn_sched_barrier(0)
; template <class Epi>
; __device__ __forceinline__ void gemm_phase(LAS unsigned char* lds, const Gemm g, const StaticOrder& S, const Epi& E, const int tid) {
;     ...
;         for (int t = 0; t < nt; t += 2) {
;     ...
;             PG8_LDA(At, 1, 1); PG8_STAGE(PG8_SB(1, 0), b3, voffB); PG8_STAGE(PG8_SB(1, 1), b3 + hstep, voffB); PG8_STAGE(PG8_SA(1, 0), a3, voffA);
;             PG8_WAIT_V(8); PG8_WAIT_L(0); PG8_BAR; PG8_MMA(1, 0, At, B0); PG8_MMA(1, 1, At, B1); PG8_BAR; PG8_SCHED;
;         }
	s_add_i32 s2, s37, s60
	s_nop 0
	v_lshl_add_u64 v[202:203], v[240:241], 0, s[86:87]
	s_mov_b32 m0, s2
	s_nop 0
	ds_read_b128 v[186:189], v176 offset:49152
	ds_read_b128 v[212:215], v176 offset:50176
	ds_read_b128 v[216:219], v176 offset:51200
	ds_read_b128 v[220:223], v176 offset:52224
	ds_read_b128 v[224:227], v176 offset:53248
	ds_read_b128 v[228:231], v176 offset:54272
	ds_read_b128 v[232:235], v176 offset:55296
	ds_read_b128 v[236:239], v176 offset:56320
	global_load_lds_dwordx4 v[202:203], off
	v_lshl_add_u64 v[202:203], v[242:243], 0, s[86:87]
	s_add_i32 m0, s2, 0x2000
	s_add_i32 s2, s38, s60
	s_nop 0
	global_load_lds_dwordx4 v[202:203], off
	v_lshl_add_u64 v[202:203], v[244:245], 0, s[86:87]
	s_mov_b32 m0, s2
	s_nop 0
	global_load_lds_dwordx4 v[202:203], off
	v_lshl_add_u64 v[202:203], v[246:247], 0, s[86:87]
	s_add_i32 m0, s2, 0x2000
	s_nop 0
	s_nop 0
	global_load_lds_dwordx4 v[202:203], off
	v_lshl_add_u64 v[202:203], v[248:249], 0, s[86:87]
	s_mov_b32 m0, s65
	s_nop 0
	global_load_lds_dwordx4 v[202:203], off
	v_lshl_add_u64 v[202:203], v[250:251], 0, s[86:87]
	s_mov_b32 m0, s66
	s_nop 0
	global_load_lds_dwordx4 v[202:203], off
	s_waitcnt vmcnt(8)
	s_waitcnt lgkmcnt(0)
	s_barrier
	s_setprio 1
	s_waitcnt lgkmcnt(0)
	s_nop 0
	v_mfma_f32_16x16x32_bf16 v[60:63], v[150:153], v[186:189], v[60:63]
	v_mfma_f32_16x16x32_bf16 v[56:59], v[158:161], v[186:189], v[56:59]
	v_mfma_f32_16x16x32_bf16 v[44:47], v[150:153], v[216:219], v[44:47]
	v_mfma_f32_16x16x32_bf16 v[40:43], v[158:161], v[216:219], v[40:43]
	v_mfma_f32_16x16x32_bf16 v[28:31], v[150:153], v[224:227], v[28:31]
	v_mfma_f32_16x16x32_bf16 v[24:27], v[158:161], v[224:227], v[24:27]
	v_mfma_f32_16x16x32_bf16 v[12:15], v[150:153], v[232:235], v[12:15]
	v_mfma_f32_16x16x32_bf16 v[8:11], v[158:161], v[232:235], v[8:11]
	v_mfma_f32_16x16x32_bf16 v[60:63], v[154:157], v[212:215], v[60:63]
	v_mfma_f32_16x16x32_bf16 v[56:59], v[162:165], v[212:215], v[56:59]
	v_mfma_f32_16x16x32_bf16 v[44:47], v[154:157], v[220:223], v[44:47]
	v_mfma_f32_16x16x32_bf16 v[40:43], v[162:165], v[220:223], v[40:43]
	v_mfma_f32_16x16x32_bf16 v[28:31], v[154:157], v[228:231], v[28:31]
	v_mfma_f32_16x16x32_bf16 v[24:27], v[162:165], v[228:231], v[24:27]
	v_mfma_f32_16x16x32_bf16 v[12:15], v[154:157], v[236:239], v[12:15]
	v_mfma_f32_16x16x32_bf16 v[8:11], v[162:165], v[236:239], v[8:11]
	s_setprio 0
	s_setprio 1
	v_mfma_f32_16x16x32_bf16 v[52:55], v[166:169], v[186:189], v[52:55]
	v_mfma_f32_16x16x32_bf16 v[48:51], v[178:181], v[186:189], v[48:51]
	v_mfma_f32_16x16x32_bf16 v[36:39], v[166:169], v[216:219], v[36:39]
	v_mfma_f32_16x16x32_bf16 v[32:35], v[178:181], v[216:219], v[32:35]
	v_mfma_f32_16x16x32_bf16 v[20:23], v[166:169], v[224:227], v[20:23]
	v_mfma_f32_16x16x32_bf16 v[16:19], v[178:181], v[224:227], v[16:19]
	v_mfma_f32_16x16x32_bf16 v[4:7], v[166:169], v[232:235], v[4:7]
	v_mfma_f32_16x16x32_bf16 v[0:3], v[178:181], v[232:235], v[0:3]
	v_mfma_f32_16x16x32_bf16 v[52:55], v[170:173], v[212:215], v[52:55]
	v_mfma_f32_16x16x32_bf16 v[48:51], v[182:185], v[212:215], v[48:51]
	v_mfma_f32_16x16x32_bf16 v[36:39], v[170:173], v[220:223], v[36:39]
	v_mfma_f32_16x16x32_bf16 v[32:35], v[182:185], v[220:223], v[32:35]
	v_mfma_f32_16x16x32_bf16 v[20:23], v[170:173], v[228:231], v[20:23]
	v_mfma_f32_16x16x32_bf16 v[16:19], v[182:185], v[228:231], v[16:19]
	v_mfma_f32_16x16x32_bf16 v[4:7], v[170:173], v[236:239], v[4:7]
	v_mfma_f32_16x16x32_bf16 v[0:3], v[182:185], v[236:239], v[0:3]
	s_setprio 0
	s_barrier
	s_add_u32 s0, s0, 0x100
	s_addc_u32 s1, s1, 0
	s_nop 0
	s_add_u32 s8, s8, 0x100
	s_addc_u32 s9, s9, 0
	s_cmp_ge_u32 s36, s67
	s_mov_b32 s2, s36
	s_cbranch_scc0 .LBB0_435
	s_and_b64 vcc, exec, s[26:27]
	s_cbranch_vccz .LBB0_438
	s_barrier
